# mixer1 prompt units: LN-section loads issued before the statistics step and its barrier (latencies overlap)
# baseline (speedup 1.0000x reference)
; __device__ __forceinline__ unsigned pk2(float lo, float hi) { return pg8::cvt_pk_bf16(lo, hi); }
; __device__ __forceinline__ void phase_mixer1(const Params& p, LAS unsigned char* lds) {
;     ...
;             if (tid < 128) {
;                 const float s1 = st1[row0 + tid], s2 = st2[row0 + tid];
;                 const float mean = s1 * (1.f / 512.f); const float var = fmaxf(s2 * (1.f / 512.f) - mean * mean, 0.f);
;                 stats[2 * tid] = mean; stats[2 * tid + 1] = __builtin_amdgcn_rsqf(var + EPS);
;             }
;             __syncthreads();
;             {
;                 const int sub = lane >> 4, c8 = (lane & 15) * 8; float g8[8], b8[8]; load8f(lng + g * 128 + c8, g8); load8f(lnb + g * 128 + c8, b8);
; #pragma unroll
;                 for (int ps = 0; ps < 4; ++ps) {
;                     const int t = 16 * wave + 4 * ps + sub; const float mean = stats[2 * t], rstd = stats[2 * t + 1];
;                     float x[8]; unpack8(*(const v4u*)(Z + (row0 + t) * NZ1 + 1024 + g * 128 + c8), x);
; #pragma unroll
;                     for (int q = 0; q < 8; ++q) { const float vn = (x[q] - mean) * rstd * g8[q] + b8[q]; vnT[vnt_off(c8 + q, t)] = (unsigned short)(pk2(vn, 0.f) & 0xffffu); }
;                 }
.LBB0_875:
	s_and_b64 vcc, exec, s[0:1]
	s_cbranch_vccz .LBB0_850
	s_ashr_i32 s50, s78, 6
	s_ashr_i32 s51, s50, 31
	s_lshl_b32 s6, s78, 5
	s_lshl_b64 s[0:1], s[50:51], 11
	s_and_b32 s9, s6, 0x780
	s_or_b32 s0, s0, s9
	s_lshr_b32 s6, s78, 7
	s_and_b32 s7, s6, 2
	v_lshl_add_u64 v[2:3], s[0:1], 0, v[118:119]
	v_mov_b64_e32 v[0:1], s[34:35]
	s_add_i32 s7, s7, s78
	v_mad_u64_u32 v[4:5], s[16:17], v2, s65, v[0:1]
	s_and_b32 s28, s7, 3
	v_mov_b32_e32 v2, v5
	s_lshl_b32 s40, s28, 9
	v_mad_u64_u32 v[2:3], s[16:17], v3, s65, v[2:3]
	v_lshl_add_u64 v[6:7], v[92:93], 0, s[40:41]
	v_lshl_add_u64 v[8:9], v[94:95], 0, s[40:41]
	v_mov_b32_e32 v5, v2
	s_lshl_b32 s40, s28, 8
	v_lshl_add_u64 v[2:3], v[4:5], 0, s[40:41]
	v_mov_b32_e32 v139, v79
	v_lshl_add_u64 v[2:3], v[2:3], 0, v[138:139]
	global_load_dwordx4 v[2:5], v[2:3], off offset:2048
	s_nop 0
	global_load_dwordx4 v[28:31], v[8:9], off
	global_load_dwordx4 v[36:39], v[6:7], off
	global_load_dwordx4 v[32:35], v[6:7], off offset:16
	global_load_dwordx4 v[24:27], v[8:9], off offset:16
	v_lshl_add_u64 v[242:243], s[0:1], 0, v[120:121]
	v_mad_u64_u32 v[244:245], s[16:17], v242, s65, v[0:1]
	v_mov_b32_e32 v242, v245
	v_mad_u64_u32 v[242:243], s[16:17], v243, s65, v[242:243]
	v_mov_b32_e32 v245, v242
	v_lshl_add_u64 v[242:243], v[244:245], 0, s[40:41]
	v_lshl_add_u64 v[242:243], v[242:243], 0, v[138:139]
	global_load_dwordx4 v[226:229], v[242:243], off offset:2048
	v_lshl_add_u64 v[242:243], s[0:1], 0, v[122:123]
	v_mad_u64_u32 v[244:245], s[16:17], v242, s65, v[0:1]
	v_mov_b32_e32 v242, v245
	v_mad_u64_u32 v[242:243], s[16:17], v243, s65, v[242:243]
	v_mov_b32_e32 v245, v242
	v_lshl_add_u64 v[242:243], v[244:245], 0, s[40:41]
	v_lshl_add_u64 v[242:243], v[242:243], 0, v[138:139]
	global_load_dwordx4 v[230:233], v[242:243], off offset:2048
	v_lshl_add_u64 v[242:243], s[0:1], 0, v[124:125]
	v_mad_u64_u32 v[244:245], s[16:17], v242, s65, v[0:1]
	v_mov_b32_e32 v242, v245
	v_mad_u64_u32 v[242:243], s[16:17], v243, s65, v[242:243]
	v_mov_b32_e32 v245, v242
	v_lshl_add_u64 v[242:243], v[244:245], 0, s[40:41]
	v_lshl_add_u64 v[242:243], v[242:243], 0, v[138:139]
	global_load_dwordx4 v[234:237], v[242:243], off offset:2048
	s_and_saveexec_b64 s[86:87], s[2:3]
	s_cbranch_execz .LBB0_878
	v_lshl_add_u64 v[246:247], s[0:1], 0, v[76:77]
	v_lshlrev_b64 v[246:247], 2, v[246:247]
	v_lshl_add_u64 v[248:249], s[26:27], 0, v[246:247]
	global_load_dword v248, v[248:249], off
	v_lshl_add_u64 v[246:247], s[38:39], 0, v[246:247]
	global_load_dword v247, v[246:247], off
	s_waitcnt vmcnt(1)
	v_mul_f32_e32 v246, 0x3b000000, v248
	v_mul_f32_e32 v248, v246, v246
	s_waitcnt vmcnt(0)
	v_fma_f32 v247, v247, s66, -v248
	v_max_f32_e32 v247, 0, v247
	v_add_f32_e32 v247, 0x358637bd, v247
	v_rsq_f32_e32 v247, v247
	ds_write_b64 v196, v[246:247]
.LBB0_878:
	s_or_b64 exec, exec, s[86:87]
	s_waitcnt lgkmcnt(0)
	s_barrier
	v_lshl_add_u64 v[8:9], s[0:1], 0, v[120:121]
	ds_read_b64 v[6:7], v197
	v_mad_u64_u32 v[10:11], s[16:17], v8, s65, v[0:1]
	v_mov_b32_e32 v8, v11
	v_mad_u64_u32 v[8:9], s[16:17], v9, s65, v[8:9]
	v_mov_b32_e32 v11, v8
	v_lshl_add_u64 v[8:9], v[10:11], 0, s[40:41]
	v_lshl_add_u64 v[8:9], v[8:9], 0, v[138:139]
	s_andn2_b64 vcc, exec, s[18:19]
	s_waitcnt vmcnt(7)
	v_lshlrev_b32_e32 v10, 16, v2
	v_and_b32_e32 v2, 0xffff0000, v2
	v_lshlrev_b32_e32 v11, 16, v3
	v_and_b32_e32 v3, 0xffff0000, v3
	v_lshlrev_b32_e32 v12, 16, v4
	v_and_b32_e32 v4, 0xffff0000, v4
	v_lshlrev_b32_e32 v13, 16, v5
	v_and_b32_e32 v5, 0xffff0000, v5
	s_waitcnt lgkmcnt(0)
	v_sub_f32_e32 v10, v10, v6
	v_sub_f32_e32 v2, v2, v6
	v_sub_f32_e32 v11, v11, v6
	v_sub_f32_e32 v3, v3, v6
	v_sub_f32_e32 v12, v12, v6
	v_sub_f32_e32 v4, v4, v6
	v_sub_f32_e32 v13, v13, v6
	v_sub_f32_e32 v5, v5, v6
	v_mul_f32_e32 v6, v7, v10
	v_mul_f32_e32 v2, v7, v2
	s_waitcnt vmcnt(5)
	v_fma_f32 v6, v36, v6, v28
	v_fma_f32 v2, v37, v2, v29
	v_mul_f32_e32 v10, v7, v11
	v_cvt_pk_bf16_f32 v6, v6, v79
	ds_write_b16 v147, v6 offset:1024
	v_cvt_pk_bf16_f32 v2, v2, v79
	v_mul_f32_e32 v3, v7, v3
	v_mul_f32_e32 v11, v7, v12
	v_mul_f32_e32 v4, v7, v4
	v_mul_f32_e32 v12, v7, v13
	v_mul_f32_e32 v5, v7, v5
	v_fma_f32 v7, v38, v10, v30
	ds_write_b16 v148, v2 offset:1024
	v_cvt_pk_bf16_f32 v2, v7, v79
	v_fma_f32 v3, v39, v3, v31
	ds_write_b16 v149, v2 offset:1024
	v_cvt_pk_bf16_f32 v2, v3, v79
	s_waitcnt vmcnt(3)
	v_fma_f32 v10, v32, v11, v24
	ds_write_b16 v150, v2 offset:1024
	v_cvt_pk_bf16_f32 v2, v10, v79
	v_fma_f32 v4, v33, v4, v25
	ds_write_b16 v151, v2 offset:1024
	v_cvt_pk_bf16_f32 v2, v4, v79
	v_fma_f32 v11, v34, v12, v26
	v_fma_f32 v5, v35, v5, v27
	ds_write_b16 v152, v2 offset:1024
	v_cvt_pk_bf16_f32 v2, v11, v79
	ds_write_b16 v153, v2 offset:1024
	v_cvt_pk_bf16_f32 v10, v5, v79
	v_lshl_add_u64 v[6:7], s[0:1], 0, v[122:123]
	v_mad_u64_u32 v[8:9], s[16:17], v6, s65, v[0:1]
	v_mov_b32_e32 v6, v9
	v_mad_u64_u32 v[6:7], s[16:17], v7, s65, v[6:7]
	v_mov_b32_e32 v9, v6
	v_lshl_add_u64 v[6:7], v[8:9], 0, s[40:41]
	ds_read_b64 v[8:9], v198
	ds_write_b16 v154, v10 offset:1024
	v_lshl_add_u64 v[6:7], v[6:7], 0, v[138:139]
	s_waitcnt vmcnt(2)
	v_mov_b32_e32 v2, v226
	v_mov_b32_e32 v3, v227
	v_mov_b32_e32 v4, v228
	v_mov_b32_e32 v5, v229
	v_lshlrev_b32_e32 v10, 16, v2
	v_and_b32_e32 v2, 0xffff0000, v2
	v_lshlrev_b32_e32 v11, 16, v3
	v_and_b32_e32 v3, 0xffff0000, v3
	v_lshlrev_b32_e32 v12, 16, v4
	v_and_b32_e32 v4, 0xffff0000, v4
	v_lshlrev_b32_e32 v13, 16, v5
	v_and_b32_e32 v5, 0xffff0000, v5
	s_waitcnt lgkmcnt(1)
; __device__ __forceinline__ unsigned pk2(float lo, float hi) { return pg8::cvt_pk_bf16(lo, hi); }
; __device__ __forceinline__ void phase_mixer1(const Params& p, LAS unsigned char* lds) {
;     ...
;                 for (int ps = 0; ps < 4; ++ps) {
;                     const int t = 16 * wave + 4 * ps + sub; const float mean = stats[2 * t], rstd = stats[2 * t + 1];
;                     float x[8]; unpack8(*(const v4u*)(Z + (row0 + t) * NZ1 + 1024 + g * 128 + c8), x);
; #pragma unroll
;                     for (int q = 0; q < 8; ++q) { const float vn = (x[q] - mean) * rstd * g8[q] + b8[q]; vnT[vnt_off(c8 + q, t)] = (unsigned short)(pk2(vn, 0.f) & 0xffffu); }
;                 }
;             }
;             __syncthreads();
;             {
;                 const int fr = lane & 15, fq = lane >> 4, t = 16 * wave + fr;
;                 f32x4 acc[8];
; #pragma unroll
;                 for (int n = 0; n < 8; ++n) acc[n] = (f32x4){0.f, 0.f, 0.f, 0.f};
;                 const bf16* wrow = Wm + (size_t)g * 16384 + t * 128;
;                 const int ksteps = (wave >> 1) + 1;
;                 for (int k = 0; k < ksteps; ++k) {
	v_sub_f32_e32 v10, v10, v8
	v_sub_f32_e32 v2, v2, v8
	v_sub_f32_e32 v11, v11, v8
	v_sub_f32_e32 v3, v3, v8
	v_sub_f32_e32 v12, v12, v8
	v_sub_f32_e32 v4, v4, v8
	v_sub_f32_e32 v13, v13, v8
	v_sub_f32_e32 v5, v5, v8
	v_mul_f32_e32 v8, v9, v10
	v_mul_f32_e32 v2, v9, v2
	v_fma_f32 v8, v36, v8, v28
	v_fma_f32 v2, v37, v2, v29
	v_mul_f32_e32 v10, v9, v11
	v_cvt_pk_bf16_f32 v8, v8, v79
	ds_write_b16 v155, v8 offset:1024
	v_cvt_pk_bf16_f32 v2, v2, v79
	v_mul_f32_e32 v3, v9, v3
	v_mul_f32_e32 v11, v9, v12
	v_mul_f32_e32 v4, v9, v4
	v_mul_f32_e32 v12, v9, v13
	v_mul_f32_e32 v5, v9, v5
	v_fma_f32 v9, v38, v10, v30
	ds_write_b16 v156, v2 offset:1024
	v_cvt_pk_bf16_f32 v2, v9, v79
	v_fma_f32 v3, v39, v3, v31
	ds_write_b16 v157, v2 offset:1024
	v_cvt_pk_bf16_f32 v2, v3, v79
	v_fma_f32 v10, v32, v11, v24
	ds_write_b16 v158, v2 offset:1024
	v_cvt_pk_bf16_f32 v2, v10, v79
	v_fma_f32 v4, v33, v4, v25
	ds_write_b16 v159, v2 offset:1024
	v_cvt_pk_bf16_f32 v2, v4, v79
	v_fma_f32 v11, v34, v12, v26
	v_fma_f32 v5, v35, v5, v27
	ds_write_b16 v160, v2 offset:1024
	v_cvt_pk_bf16_f32 v2, v11, v79
	ds_write_b16 v161, v2 offset:1024
	v_cvt_pk_bf16_f32 v8, v5, v79
	v_lshl_add_u64 v[6:7], s[0:1], 0, v[124:125]
	v_mad_u64_u32 v[0:1], s[16:17], v6, s65, v[0:1]
	v_mov_b32_e32 v6, v1
	v_mad_u64_u32 v[6:7], s[16:17], v7, s65, v[6:7]
	v_mov_b32_e32 v1, v6
	ds_read_b64 v[6:7], v199
	ds_write_b16 v162, v8 offset:1024
	v_lshl_add_u64 v[0:1], v[0:1], 0, s[40:41]
	v_lshl_add_u64 v[0:1], v[0:1], 0, v[138:139]
	s_waitcnt vmcnt(1)
	v_mov_b32_e32 v2, v230
	v_mov_b32_e32 v3, v231
	v_mov_b32_e32 v4, v232
	v_mov_b32_e32 v5, v233
	v_lshlrev_b32_e32 v8, 16, v2
	v_and_b32_e32 v2, 0xffff0000, v2
	v_lshlrev_b32_e32 v9, 16, v3
	v_and_b32_e32 v3, 0xffff0000, v3
	v_lshlrev_b32_e32 v10, 16, v4
	v_and_b32_e32 v4, 0xffff0000, v4
	v_lshlrev_b32_e32 v11, 16, v5
	v_and_b32_e32 v5, 0xffff0000, v5
	s_waitcnt lgkmcnt(1)
	v_sub_f32_e32 v8, v8, v6
	v_sub_f32_e32 v2, v2, v6
	v_sub_f32_e32 v9, v9, v6
	v_sub_f32_e32 v3, v3, v6
	v_sub_f32_e32 v10, v10, v6
	v_sub_f32_e32 v4, v4, v6
	v_sub_f32_e32 v11, v11, v6
	v_sub_f32_e32 v5, v5, v6
	v_mul_f32_e32 v6, v7, v8
	v_mul_f32_e32 v2, v7, v2
	v_fma_f32 v6, v36, v6, v28
	v_fma_f32 v2, v37, v2, v29
	v_mul_f32_e32 v8, v7, v9
	v_cvt_pk_bf16_f32 v6, v6, v79
	ds_write_b16 v163, v6 offset:1024
	v_cvt_pk_bf16_f32 v2, v2, v79
	v_mul_f32_e32 v3, v7, v3
	v_mul_f32_e32 v9, v7, v10
	v_mul_f32_e32 v4, v7, v4
	v_mul_f32_e32 v10, v7, v11
	v_mul_f32_e32 v5, v7, v5
	v_fma_f32 v7, v38, v8, v30
	ds_write_b16 v164, v2 offset:1024
	v_cvt_pk_bf16_f32 v2, v7, v79
	v_fma_f32 v3, v39, v3, v31
	ds_write_b16 v165, v2 offset:1024
	v_cvt_pk_bf16_f32 v2, v3, v79
	v_fma_f32 v8, v32, v9, v24
	ds_write_b16 v166, v2 offset:1024
	v_cvt_pk_bf16_f32 v2, v8, v79
	v_fma_f32 v4, v33, v4, v25
	ds_write_b16 v167, v2 offset:1024
	v_cvt_pk_bf16_f32 v2, v4, v79
	v_fma_f32 v9, v34, v10, v26
	v_fma_f32 v5, v35, v5, v27
	ds_write_b16 v168, v2 offset:1024
	v_cvt_pk_bf16_f32 v2, v9, v79
	ds_write_b16 v169, v2 offset:1024
	v_cvt_pk_bf16_f32 v44, v5, v79
	ds_read_b64 v[52:53], v200
	ds_write_b16 v170, v44 offset:1024
	v_mov_b32_e32 v3, 0
	v_mov_b32_e32 v2, v3
	v_mov_b32_e32 v1, v3
	v_mov_b32_e32 v0, v3
	v_mov_b32_e32 v7, v3
	v_mov_b32_e32 v6, v3
	v_mov_b32_e32 v5, v3
	v_mov_b32_e32 v4, v3
	v_mov_b32_e32 v11, v3
	v_mov_b32_e32 v10, v3
	v_mov_b32_e32 v9, v3
	v_mov_b32_e32 v8, v3
	v_mov_b32_e32 v15, v3
	v_mov_b32_e32 v14, v3
	v_mov_b32_e32 v13, v3
	v_mov_b32_e32 v12, v3
	v_mov_b32_e32 v19, v3
	v_mov_b32_e32 v18, v3
	v_mov_b32_e32 v17, v3
	v_mov_b32_e32 v16, v3
	v_mov_b32_e32 v23, v3
	v_mov_b32_e32 v22, v3
	v_mov_b32_e32 v21, v3
	v_mov_b32_e32 v20, v3
	v_mov_b32_e32 v43, v3
	v_mov_b32_e32 v42, v3
	v_mov_b32_e32 v41, v3
	v_mov_b32_e32 v40, v3
	v_mov_b32_e32 v47, v3
	v_mov_b32_e32 v46, v3
	v_mov_b32_e32 v45, v3
	s_waitcnt vmcnt(0)
	v_mov_b32_e32 v48, v234
	v_mov_b32_e32 v49, v235
	v_mov_b32_e32 v50, v236
	v_mov_b32_e32 v51, v237
	v_lshlrev_b32_e32 v44, 16, v48
	s_waitcnt lgkmcnt(1)
	v_sub_f32_e32 v44, v44, v52
	v_and_b32_e32 v48, 0xffff0000, v48
	v_mul_f32_e32 v44, v53, v44
	v_lshlrev_b32_e32 v54, 16, v49
	v_lshlrev_b32_e32 v55, 16, v50
	v_sub_f32_e32 v48, v48, v52
	v_fma_f32 v28, v36, v44, v28
	v_and_b32_e32 v49, 0xffff0000, v49
	v_and_b32_e32 v50, 0xffff0000, v50
	v_lshlrev_b32_e32 v56, 16, v51
	v_and_b32_e32 v51, 0xffff0000, v51
	v_sub_f32_e32 v54, v54, v52
	v_sub_f32_e32 v55, v55, v52
	v_mul_f32_e32 v48, v53, v48
	v_cvt_pk_bf16_f32 v28, v28, v79
	v_sub_f32_e32 v49, v49, v52
	v_sub_f32_e32 v50, v50, v52
	v_sub_f32_e32 v56, v56, v52
	v_sub_f32_e32 v51, v51, v52
	v_mul_f32_e32 v52, v53, v54
	v_mul_f32_e32 v54, v53, v55
	v_fma_f32 v29, v37, v48, v29
	ds_write_b16 v171, v28 offset:1024
	v_cvt_pk_bf16_f32 v28, v29, v79
	v_mul_f32_e32 v49, v53, v49
	v_fma_f32 v30, v38, v52, v30
	v_fma_f32 v24, v32, v54, v24
	ds_write_b16 v172, v28 offset:1024
	v_cvt_pk_bf16_f32 v28, v30, v79
	v_mul_f32_e32 v50, v53, v50
	v_fmac_f32_e32 v31, v39, v49
	ds_write_b16 v173, v28 offset:1024
	v_cvt_pk_bf16_f32 v28, v31, v79
	ds_write_b16 v174, v28 offset:1024
	v_cvt_pk_bf16_f32 v24, v24, v79
	v_mul_f32_e32 v55, v53, v56
	v_fma_f32 v25, v33, v50, v25
	ds_write_b16 v175, v24 offset:1024
	v_cvt_pk_bf16_f32 v24, v25, v79
	v_mul_f32_e32 v51, v53, v51
	v_fma_f32 v26, v34, v55, v26
	ds_write_b16 v176, v24 offset:1024
	v_cvt_pk_bf16_f32 v24, v26, v79
	v_mov_b32_e32 v44, v3
	v_fmac_f32_e32 v27, v35, v51
	ds_write_b16 v177, v24 offset:1024
	v_cvt_pk_bf16_f32 v24, v27, v79
	ds_write_b16 v178, v24 offset:1024
	s_waitcnt lgkmcnt(0)
	s_barrier
	s_cbranch_vccnz .LBB0_881
	s_and_b32 s6, s6, 0x1fffffe
	s_add_i32 s6, s6, s77
	s_and_b32 s6, s6, 3
	s_lshl_b32 s40, s6, 15
	v_mov_b32_e32 v44, 0
	v_lshl_add_u64 v[24:25], v[136:137], 0, s[40:41]
	v_mov_b32_e32 v26, v143
	s_mov_b32 s6, s64
	v_mov_b32_e32 v45, v44
	v_mov_b32_e32 v46, v44
	v_mov_b32_e32 v47, v44
	v_mov_b32_e32 v40, v44
	v_mov_b32_e32 v41, v44
	v_mov_b32_e32 v42, v44
	v_mov_b32_e32 v43, v44
	v_mov_b32_e32 v20, v44
	v_mov_b32_e32 v21, v44
	v_mov_b32_e32 v22, v44
	v_mov_b32_e32 v23, v44
	v_mov_b32_e32 v16, v44
	v_mov_b32_e32 v17, v44
	v_mov_b32_e32 v18, v44
	v_mov_b32_e32 v19, v44
	v_mov_b32_e32 v12, v44
	v_mov_b32_e32 v13, v44
	v_mov_b32_e32 v14, v44
	v_mov_b32_e32 v15, v44
	v_mov_b32_e32 v8, v44
	v_mov_b32_e32 v9, v44
	v_mov_b32_e32 v10, v44
	v_mov_b32_e32 v11, v44
	v_mov_b32_e32 v4, v44
	v_mov_b32_e32 v5, v44
	v_mov_b32_e32 v6, v44
	v_mov_b32_e32 v7, v44
	v_mov_b32_e32 v0, v44
	v_mov_b32_e32 v1, v44
	v_mov_b32_e32 v2, v44
	v_mov_b32_e32 v3, v44
